# nt hint on read-once f32 weight loads; out-proj and odd in-proj weight transposes moved from the prologue into the idle tail of the even in-projection (workgroups with 12 instead of 13 tiles), hand-wr
# speedup vs baseline: 1.0208x; 1.0089x over previous
; __device__ __forceinline__ unsigned cvt_pk_bf16(float lo, float hi) { unsigned r; asm volatile("v_cvt_pk_bf16_f32 %0, %1, %2" : "=v"(r) : "v"(lo), "v"(hi)); return r; }
;     const long total = (long)(K / 8) * Ndst;
; #pragma unroll 4
;     for (long it = gtid; it < total; it += gsz) {
;         const int n = (int)(it % Ndst), k8 = (int)(it / Ndst);
;         int sc = n;
;         if (MODE == 1) { if (n < 3584) sc = n; else sc = n + 16; }
;         u32x4 w = {0u, 0u, 0u, 0u};
;         if (sc >= 0) {
;             const float* s = src + (size_t)(k8 * 8) * Nsrc + sc;
;             float v0 = s[0], v1 = s[(size_t)Nsrc], v2 = s[(size_t)2 * Nsrc], v3 = s[(size_t)3 * Nsrc], v4 = s[(size_t)4 * Nsrc], v5 = s[(size_t)5 * Nsrc], v6 = s[(size_t)6 * Nsrc], v7 = s[(size_t)7 * Nsrc];
;             if (gain) { const f32x4 g0 = *(const f32x4*)(gain + k8 * 8), g1 = *(const f32x4*)(gain + k8 * 8 + 4); v0 *= g0[0]; v1 *= g0[1]; v2 *= g0[2]; v3 *= g0[3]; v4 *= g1[0]; v5 *= g1[1]; v6 *= g1[2]; v7 *= g1[3]; }
;             w.x = cvt_pk_bf16(v0 * wscale, v1 * wscale); w.y = cvt_pk_bf16(v2 * wscale, v3 * wscale); w.z = cvt_pk_bf16(v4 * wscale, v5 * wscale); w.w = cvt_pk_bf16(v6 * wscale, v7 * wscale);
;         }
;         *(u32x4*)(dst + (size_t)n * K + k8 * 8) = w;
;     }
; }
; __device__ __forceinline__ void phase0(const Params& p) {
;     ...
;     transpose_w<1>(p.in[8], 1024, 5648, (bf16_t*)(ws + WS_WINE), 5632, p.in[7], gtid, gsz);
.LBB0_21:
	v_mul_hi_u32 v0, v4, s16
	v_lshrrev_b32_e32 v16, 12, v0
	v_mul_u32_u24_e32 v0, 0x1600, v16
	v_sub_u32_e32 v0, v4, v0
	v_add_u32_e32 v6, 16, v0
	v_cmp_gt_u32_e32 vcc, s17, v0
	v_mov_b32_e32 v7, v1
	v_mad_u64_u32 v[10:11], s[24:25], v16, s18, v[2:3]
	v_cndmask_b32_e32 v6, v6, v0, vcc
	v_lshl_add_u64 v[6:7], v[6:7], 2, v[10:11]
	v_add_co_u32_e32 v10, vcc, s19, v6
	s_nop 1
	v_addc_co_u32_e32 v11, vcc, 0, v7, vcc
	v_add_co_u32_e32 v12, vcc, s20, v6
	s_nop 1
	v_addc_co_u32_e32 v13, vcc, 0, v7, vcc
	v_add_co_u32_e32 v14, vcc, s21, v6
	s_nop 1
	v_addc_co_u32_e32 v15, vcc, 0, v7, vcc
	v_add_co_u32_e32 v18, vcc, s22, v6
	s_nop 1
	v_addc_co_u32_e32 v19, vcc, 0, v7, vcc
	v_add_co_u32_e32 v20, vcc, 0x1b000, v6
	s_nop 1
	v_addc_co_u32_e32 v21, vcc, 0, v7, vcc
	v_add_co_u32_e32 v22, vcc, 0x21000, v6
	s_nop 1
	v_addc_co_u32_e32 v23, vcc, 0, v7, vcc
	v_add_co_u32_e32 v24, vcc, 0x26000, v6
	s_nop 1
	v_addc_co_u32_e32 v25, vcc, 0, v7, vcc
	global_load_dword v6, v[6:7], off nt
	s_nop 0
	global_load_dword v7, v[10:11], off offset:2112 nt
	s_nop 0
	global_load_dword v10, v[12:13], off offset:128 nt
	global_load_dword v11, v[14:15], off offset:2240 nt
	s_nop 0
	global_load_dword v14, v[18:19], off offset:256 nt
	global_load_dword v15, v[20:21], off offset:2368 nt
	global_load_dword v12, v[22:23], off offset:384 nt
	global_load_dword v13, v[24:25], off offset:2496 nt
	s_and_b64 vcc, exec, s[0:1]
	s_cbranch_vccnz .LBB0_20
	v_readlane_b32 s48, v250, 4
	v_lshlrev_b32_e32 v17, 5, v16
	v_readlane_b32 s62, v250, 18
	v_readlane_b32 s63, v250, 19
	s_nop 4
	global_load_dwordx4 v[18:21], v17, s[62:63]
	global_load_dwordx4 v[22:25], v17, s[62:63] offset:16
	v_readlane_b32 s49, v250, 5
	v_readlane_b32 s50, v250, 6
	v_readlane_b32 s51, v250, 7
	v_readlane_b32 s52, v250, 8
	v_readlane_b32 s53, v250, 9
	v_readlane_b32 s54, v250, 10
	v_readlane_b32 s55, v250, 11
	v_readlane_b32 s56, v250, 12
	v_readlane_b32 s57, v250, 13
	v_readlane_b32 s58, v250, 14
	v_readlane_b32 s59, v250, 15
	v_readlane_b32 s60, v250, 16
	v_readlane_b32 s61, v250, 17
	s_waitcnt vmcnt(1)
	v_pk_mul_f32 v[6:7], v[6:7], v[18:19]
	v_pk_mul_f32 v[10:11], v[10:11], v[20:21]
	s_waitcnt vmcnt(0)
	v_pk_mul_f32 v[14:15], v[14:15], v[22:23]
	v_pk_mul_f32 v[12:13], v[12:13], v[24:25]
	s_branch .LBB0_20

; __device__ __forceinline__ unsigned cvt_pk_bf16(float lo, float hi) { unsigned r; asm volatile("v_cvt_pk_bf16_f32 %0, %1, %2" : "=v"(r) : "v"(lo), "v"(hi)); return r; }
; __device__ __forceinline__ void phase0(const Params& p) {
;     ...
;     for (long it = gtid; it < 128L * 512; it += gsz) {
;         const int n = (int)(it & 511), k8 = (int)(it >> 9);
;         float wl[16];
; #pragma unroll
;         for (int r = 0; r < 16; ++r) wl[r] = p.in[9][r * 512 + n];
;         float v[8];
; #pragma unroll
;         for (int i = 0; i < 8; ++i) {
;             const float* wr_ = p.in[8] + (size_t)(k8 * 8 + i) * 5648 + 3584;
;             float a = 0.f;
; #pragma unroll
;             for (int r4 = 0; r4 < 4; ++r4) { const f32x4 x = *(const f32x4*)(wr_ + r4 * 4); a += x[0] * wl[r4 * 4] + x[1] * wl[r4 * 4 + 1] + x[2] * wl[r4 * 4 + 2] + x[3] * wl[r4 * 4 + 3]; }
;             v[i] = a * p.in[7][k8 * 8 + i];
;         }
;         u32x4 w; w.x = cvt_pk_bf16(v[0], v[1]); w.y = cvt_pk_bf16(v[2], v[3]); w.z = cvt_pk_bf16(v[4], v[5]); w.w = cvt_pk_bf16(v[6], v[7]);
;         *(u32x4*)((bf16_t*)(ws + WS_WINE) + (size_t)(5632 + n) * 1024 + k8 * 8) = w;
;     }
.LBB0_25:
	v_alignbit_b32 v2, v49, v48, 9
	v_lshrrev_b64 v[0:1], 9, v[48:49]
	v_lshl_add_u64 v[48:49], v[48:49], 0, s[6:7]
	v_lshlrev_b32_e32 v10, 3, v2
	v_lshl_add_u64 v[66:67], v[0:1], 4, v[12:13]
	v_cmp_lt_u64_e32 vcc, s[14:15], v[48:49]
	v_mad_u64_u32 v[0:1], s[18:19], v10, s16, v[46:47]
	v_or_b32_e32 v70, 1, v10
	s_or_b64 s[10:11], vcc, s[10:11]
	v_add_co_u32_e32 v68, vcc, s17, v0
	v_mad_u64_u32 v[84:85], s[18:19], v70, s16, v[46:47]
	s_nop 0
	v_addc_co_u32_e32 v69, vcc, 0, v1, vcc
	v_or_b32_e32 v71, 2, v10
	v_lshl_add_u64 v[98:99], v[84:85], 0, s[12:13]
	v_add_co_u32_e32 v84, vcc, s17, v84
	v_mad_u64_u32 v[86:87], s[18:19], v71, s16, v[46:47]
	s_nop 0
	v_addc_co_u32_e32 v85, vcc, 0, v85, vcc
	v_or_b32_e32 v72, 3, v10
	v_add_co_u32_e32 v100, vcc, s17, v86
	v_mad_u64_u32 v[88:89], s[18:19], v72, s16, v[46:47]
	s_nop 0
	v_addc_co_u32_e32 v101, vcc, 0, v87, vcc
	v_or_b32_e32 v73, 4, v10
	v_add_co_u32_e32 v116, vcc, s17, v88
	v_mad_u64_u32 v[90:91], s[18:19], v73, s16, v[46:47]
	s_nop 0
	v_addc_co_u32_e32 v117, vcc, 0, v89, vcc
	v_or_b32_e32 v74, 5, v10
	v_add_co_u32_e32 v132, vcc, s17, v90
	v_mad_u64_u32 v[92:93], s[18:19], v74, s16, v[46:47]
	s_nop 0
	v_addc_co_u32_e32 v133, vcc, 0, v91, vcc
	v_or_b32_e32 v75, 6, v10
	v_add_co_u32_e32 v150, vcc, s17, v92
	v_mad_u64_u32 v[94:95], s[18:19], v75, s16, v[46:47]
	s_nop 0
	v_addc_co_u32_e32 v151, vcc, 0, v93, vcc
	v_lshl_add_u64 v[4:5], v[10:11], 2, s[26:27]
	v_or_b32_e32 v10, 7, v10
	v_add_co_u32_e32 v166, vcc, s17, v94
	v_mad_u64_u32 v[96:97], s[18:19], v10, s16, v[46:47]
	s_nop 0
	v_addc_co_u32_e32 v167, vcc, 0, v95, vcc
	v_lshl_add_u64 v[80:81], v[0:1], 0, s[12:13]
	v_add_co_u32_e32 v182, vcc, s17, v96
	global_load_dword v58, v[14:15], off nt
	global_load_dword v62, v[16:17], off nt
	global_load_dword v54, v[18:19], off nt
	global_load_dword v50, v[20:21], off nt
	global_load_dword v59, v[22:23], off nt
	global_load_dword v63, v[24:25], off nt
	global_load_dword v55, v[26:27], off nt
	global_load_dword v51, v[28:29], off nt
	global_load_dword v60, v[30:31], off nt
	global_load_dword v64, v[32:33], off nt
	global_load_dword v56, v[34:35], off nt
	global_load_dword v52, v[36:37], off nt
	global_load_dword v61, v[38:39], off nt
	global_load_dword v65, v[40:41], off nt
	global_load_dword v57, v[42:43], off nt
	global_load_dword v53, v[44:45], off nt
	global_load_dwordx4 v[0:3], v[4:5], off offset:16
	s_nop 0
	global_load_dwordx4 v[4:7], v[4:5], off
	s_nop 0
	global_load_dwordx4 v[68:71], v[68:69], off offset:2048
	s_nop 0
	global_load_dwordx4 v[72:75], v[80:81], off offset:48
	global_load_dwordx4 v[76:79], v[80:81], off offset:32
	s_nop 0
	global_load_dwordx4 v[80:83], v[80:81], off offset:16
	v_lshl_add_u64 v[112:113], v[86:87], 0, s[12:13]
	v_lshl_add_u64 v[128:129], v[88:89], 0, s[12:13]
	v_lshl_add_u64 v[146:147], v[90:91], 0, s[12:13]
	v_lshl_add_u64 v[162:163], v[92:93], 0, s[12:13]
	v_lshl_add_u64 v[178:179], v[94:95], 0, s[12:13]
	v_lshl_add_u64 v[194:195], v[96:97], 0, s[12:13]
	v_addc_co_u32_e32 v183, vcc, 0, v97, vcc
	global_load_dwordx4 v[84:87], v[84:85], off offset:2048
	s_nop 0
	global_load_dwordx4 v[88:91], v[98:99], off offset:16
	global_load_dwordx4 v[92:95], v[98:99], off offset:32
	s_nop 0
	global_load_dwordx4 v[96:99], v[98:99], off offset:48
	s_nop 0
	global_load_dwordx4 v[100:103], v[100:101], off offset:2048
	s_nop 0
	global_load_dwordx4 v[104:107], v[112:113], off offset:16
	global_load_dwordx4 v[108:111], v[112:113], off offset:32
	s_nop 0
	global_load_dwordx4 v[112:115], v[112:113], off offset:48
	s_nop 0
	global_load_dwordx4 v[116:119], v[116:117], off offset:2048
	s_nop 0
	global_load_dwordx4 v[120:123], v[128:129], off offset:16
	global_load_dwordx4 v[124:127], v[128:129], off offset:32
	s_nop 0
	global_load_dwordx4 v[128:131], v[128:129], off offset:48
	s_nop 0
	global_load_dwordx4 v[132:135], v[132:133], off offset:2048
	s_nop 0
	global_load_dwordx4 v[138:141], v[146:147], off offset:16
	global_load_dwordx4 v[142:145], v[146:147], off offset:32
	s_nop 0
	global_load_dwordx4 v[146:149], v[146:147], off offset:48
	s_nop 0
	global_load_dwordx4 v[150:153], v[150:151], off offset:2048
	s_nop 0
	global_load_dwordx4 v[154:157], v[162:163], off offset:16
	global_load_dwordx4 v[158:161], v[162:163], off offset:32
	s_nop 0
	global_load_dwordx4 v[162:165], v[162:163], off offset:48
	s_nop 0
	global_load_dwordx4 v[166:169], v[166:167], off offset:2048
	s_nop 0
	global_load_dwordx4 v[170:173], v[178:179], off offset:48
	global_load_dwordx4 v[174:177], v[178:179], off offset:32
	s_nop 0
	global_load_dwordx4 v[178:181], v[178:179], off offset:16
	s_nop 0
	global_load_dwordx4 v[182:185], v[182:183], off offset:2048
	s_nop 0
	global_load_dwordx4 v[186:189], v[194:195], off offset:48
	global_load_dwordx4 v[190:193], v[194:195], off offset:32
	s_nop 0
	global_load_dwordx4 v[194:197], v[194:195], off offset:16
	s_waitcnt vmcnt(31)
	v_mov_b32_e32 v198, v68
	v_mov_b32_e32 v68, v70
	s_waitcnt vmcnt(29)
	v_mov_b32_e32 v70, v76
	s_waitcnt vmcnt(28)
	v_mov_b32_e32 v199, v80
	v_mov_b32_e32 v80, v69
	v_mov_b32_e32 v69, v82
	v_mov_b32_e32 v82, v71
	v_mov_b32_e32 v71, v72
	v_mov_b32_e32 v72, v77
	v_mov_b32_e32 v76, v78
	v_mov_b32_e32 v77, v74
	v_mov_b32_e32 v74, v79
	v_pk_mul_f32 v[78:79], v[62:63], v[80:81]
	v_pk_mul_f32 v[72:73], v[64:65], v[72:73]
	s_waitcnt vmcnt(26)
	v_mov_b32_e32 v81, v88
	v_mov_b32_e32 v88, v85
	v_mov_b32_e32 v85, v90
	v_mov_b32_e32 v90, v87
	s_waitcnt vmcnt(24)
	v_mov_b32_e32 v87, v96
	v_mov_b32_e32 v96, v93
	v_mov_b32_e32 v93, v98
	v_mov_b32_e32 v98, v95
	s_waitcnt vmcnt(22)
	v_mov_b32_e32 v95, v104
	v_mov_b32_e32 v104, v101
	v_mov_b32_e32 v101, v106
	v_mov_b32_e32 v106, v103
	s_waitcnt vmcnt(20)
; __device__ __forceinline__ unsigned cvt_pk_bf16(float lo, float hi) { unsigned r; asm volatile("v_cvt_pk_bf16_f32 %0, %1, %2" : "=v"(r) : "v"(lo), "v"(hi)); return r; }
; __device__ __forceinline__ void phase0(const Params& p) {
;     ...
;         for (int r = 0; r < 16; ++r) wl[r] = p.in[9][r * 512 + n];
;         float v[8];
; #pragma unroll
;         for (int i = 0; i < 8; ++i) {
;             const float* wr_ = p.in[8] + (size_t)(k8 * 8 + i) * 5648 + 3584;
;             float a = 0.f;
; #pragma unroll
;             for (int r4 = 0; r4 < 4; ++r4) { const f32x4 x = *(const f32x4*)(wr_ + r4 * 4); a += x[0] * wl[r4 * 4] + x[1] * wl[r4 * 4 + 1] + x[2] * wl[r4 * 4 + 2] + x[3] * wl[r4 * 4 + 3]; }
;             v[i] = a * p.in[7][k8 * 8 + i];
;         }
;         u32x4 w; w.x = cvt_pk_bf16(v[0], v[1]); w.y = cvt_pk_bf16(v[2], v[3]); w.z = cvt_pk_bf16(v[4], v[5]); w.w = cvt_pk_bf16(v[6], v[7]);
;         *(u32x4*)((bf16_t*)(ws + WS_WINE) + (size_t)(5632 + n) * 1024 + k8 * 8) = w;
	v_mov_b32_e32 v103, v112
	v_mov_b32_e32 v112, v109
	v_mov_b32_e32 v109, v114
	v_mov_b32_e32 v114, v111
	s_waitcnt vmcnt(18)
	v_mov_b32_e32 v111, v120
	v_mov_b32_e32 v120, v117
	v_mov_b32_e32 v117, v122
	v_mov_b32_e32 v122, v119
	s_waitcnt vmcnt(16)
	v_mov_b32_e32 v119, v128
	v_mov_b32_e32 v128, v125
	v_mov_b32_e32 v125, v130
	v_mov_b32_e32 v130, v127
	s_waitcnt vmcnt(14)
	v_mov_b32_e32 v127, v138
	v_mov_b32_e32 v138, v133
	v_mov_b32_e32 v133, v140
	v_mov_b32_e32 v140, v135
	s_waitcnt vmcnt(12)
	v_mov_b32_e32 v135, v146
	v_mov_b32_e32 v146, v143
	v_mov_b32_e32 v143, v148
	v_mov_b32_e32 v148, v145
	s_waitcnt vmcnt(10)
	v_mov_b32_e32 v145, v154
	v_mov_b32_e32 v154, v151
	v_mov_b32_e32 v151, v156
	v_mov_b32_e32 v156, v153
	s_waitcnt vmcnt(8)
	v_mov_b32_e32 v153, v162
	v_mov_b32_e32 v162, v159
	v_mov_b32_e32 v159, v164
	v_mov_b32_e32 v164, v161
	s_waitcnt vmcnt(4)
	v_mov_b32_e32 v161, v178
	v_mov_b32_e32 v178, v167
	v_mov_b32_e32 v167, v180
	v_mov_b32_e32 v180, v169
	v_mov_b32_e32 v169, v170
	v_mov_b32_e32 v170, v175
	v_mov_b32_e32 v175, v172
	v_mov_b32_e32 v172, v177
	s_waitcnt vmcnt(0)
	v_mov_b32_e32 v177, v194
	v_mov_b32_e32 v194, v183
	v_mov_b32_e32 v80, v84
	v_mov_b32_e32 v84, v86
	v_mov_b32_e32 v86, v92
	v_mov_b32_e32 v92, v94
	v_mov_b32_e32 v94, v100
	v_mov_b32_e32 v100, v102
	v_mov_b32_e32 v102, v108
	v_mov_b32_e32 v108, v110
	v_mov_b32_e32 v110, v116
	v_mov_b32_e32 v116, v118
	v_mov_b32_e32 v118, v124
	v_mov_b32_e32 v124, v126
	v_mov_b32_e32 v126, v132
	v_mov_b32_e32 v132, v134
	v_mov_b32_e32 v134, v142
	v_mov_b32_e32 v142, v144
	v_mov_b32_e32 v144, v150
	v_mov_b32_e32 v150, v152
	v_mov_b32_e32 v152, v158
	v_mov_b32_e32 v158, v160
	v_mov_b32_e32 v160, v166
	v_mov_b32_e32 v166, v168
	v_mov_b32_e32 v168, v174
	v_mov_b32_e32 v174, v176
	v_mov_b32_e32 v176, v182
	v_mov_b32_e32 v183, v196
	v_mov_b32_e32 v196, v185
	v_mov_b32_e32 v185, v186
	v_mov_b32_e32 v186, v191
	v_pk_fma_f32 v[78:79], v[58:59], v[198:199], v[78:79]
	v_pk_fma_f32 v[70:71], v[60:61], v[70:71], v[72:73]
	v_pk_mul_f32 v[72:73], v[62:63], v[88:89]
	v_pk_mul_f32 v[88:89], v[64:65], v[96:97]
	v_pk_mul_f32 v[96:97], v[62:63], v[104:105]
	v_pk_mul_f32 v[104:105], v[64:65], v[112:113]
	v_pk_mul_f32 v[112:113], v[62:63], v[120:121]
	v_pk_mul_f32 v[120:121], v[64:65], v[128:129]
	v_pk_mul_f32 v[128:129], v[62:63], v[138:139]
	v_pk_mul_f32 v[138:139], v[64:65], v[146:147]
	v_pk_mul_f32 v[146:147], v[62:63], v[154:155]
	v_pk_mul_f32 v[154:155], v[64:65], v[162:163]
	v_pk_mul_f32 v[162:163], v[62:63], v[178:179]
	v_pk_mul_f32 v[62:63], v[62:63], v[194:195]
	v_mov_b32_e32 v182, v184
	v_mov_b32_e32 v184, v190
	v_pk_mul_f32 v[170:171], v[64:65], v[170:171]
	v_pk_mul_f32 v[64:65], v[64:65], v[186:187]
	v_pk_fma_f32 v[68:69], v[54:55], v[68:69], v[78:79]
	v_pk_fma_f32 v[70:71], v[56:57], v[76:77], v[70:71]
	v_pk_fma_f32 v[72:73], v[58:59], v[80:81], v[72:73]
	v_pk_fma_f32 v[76:77], v[60:61], v[86:87], v[88:89]
	v_pk_fma_f32 v[78:79], v[58:59], v[94:95], v[96:97]
	v_pk_fma_f32 v[80:81], v[60:61], v[102:103], v[104:105]
	v_pk_fma_f32 v[86:87], v[58:59], v[110:111], v[112:113]
	v_pk_fma_f32 v[88:89], v[60:61], v[118:119], v[120:121]
	v_pk_fma_f32 v[94:95], v[58:59], v[126:127], v[128:129]
	v_pk_fma_f32 v[102:103], v[58:59], v[144:145], v[146:147]
	v_pk_fma_f32 v[110:111], v[58:59], v[160:161], v[162:163]
	v_pk_fma_f32 v[58:59], v[58:59], v[176:177], v[62:63]
	v_pk_fma_f32 v[96:97], v[60:61], v[134:135], v[138:139]
	v_pk_fma_f32 v[104:105], v[60:61], v[152:153], v[154:155]
	v_pk_fma_f32 v[112:113], v[60:61], v[168:169], v[170:171]
	v_pk_fma_f32 v[60:61], v[60:61], v[184:185], v[64:65]
	v_pk_fma_f32 v[62:63], v[50:51], v[82:83], v[68:69]
	v_pk_fma_f32 v[64:65], v[52:53], v[74:75], v[70:71]
	v_pk_fma_f32 v[68:69], v[54:55], v[84:85], v[72:73]
	v_pk_fma_f32 v[70:71], v[56:57], v[92:93], v[76:77]
	v_pk_fma_f32 v[72:73], v[54:55], v[100:101], v[78:79]
	v_pk_fma_f32 v[74:75], v[56:57], v[108:109], v[80:81]
	v_pk_fma_f32 v[76:77], v[54:55], v[116:117], v[86:87]
	v_pk_fma_f32 v[78:79], v[56:57], v[124:125], v[88:89]
	v_pk_fma_f32 v[80:81], v[54:55], v[132:133], v[94:95]
	v_pk_fma_f32 v[84:85], v[54:55], v[150:151], v[102:103]
	v_pk_fma_f32 v[88:89], v[54:55], v[166:167], v[110:111]
	v_pk_fma_f32 v[54:55], v[54:55], v[182:183], v[58:59]
	v_mov_b32_e32 v190, v192
	v_mov_b32_e32 v191, v188
	v_pk_fma_f32 v[58:59], v[50:51], v[90:91], v[68:69]
	v_pk_fma_f32 v[68:69], v[50:51], v[106:107], v[72:73]
	v_pk_fma_f32 v[72:73], v[50:51], v[122:123], v[76:77]
	v_pk_fma_f32 v[76:77], v[50:51], v[140:141], v[80:81]
	v_pk_fma_f32 v[80:81], v[50:51], v[156:157], v[84:85]
	v_pk_fma_f32 v[84:85], v[50:51], v[180:181], v[88:89]
	v_pk_fma_f32 v[50:51], v[50:51], v[196:197], v[54:55]
	v_mov_b32_e32 v188, v193
	v_pk_fma_f32 v[82:83], v[56:57], v[142:143], v[96:97]
	v_pk_fma_f32 v[86:87], v[56:57], v[158:159], v[104:105]
	v_pk_fma_f32 v[92:93], v[56:57], v[174:175], v[112:113]
	v_pk_fma_f32 v[56:57], v[56:57], v[190:191], v[60:61]
	v_add_f32_e32 v10, 0, v62
	v_add_f32_e32 v50, 0, v50
	v_pk_fma_f32 v[60:61], v[52:53], v[98:99], v[70:71]
	v_pk_fma_f32 v[70:71], v[52:53], v[114:115], v[74:75]
	v_pk_fma_f32 v[74:75], v[52:53], v[130:131], v[78:79]
	v_pk_fma_f32 v[78:79], v[52:53], v[148:149], v[82:83]
	v_pk_fma_f32 v[82:83], v[52:53], v[164:165], v[86:87]
	v_pk_fma_f32 v[86:87], v[52:53], v[172:173], v[92:93]
	v_pk_fma_f32 v[52:53], v[52:53], v[188:189], v[56:57]
	v_add_f32_e32 v10, v10, v63
	v_add_f32_e32 v54, 0, v58
	v_add_f32_e32 v55, 0, v68
	v_add_f32_e32 v56, 0, v72
	v_add_f32_e32 v57, 0, v76
	v_add_f32_e32 v58, 0, v80
	v_add_f32_e32 v62, 0, v84
	v_add_f32_e32 v50, v50, v51
	v_add_f32_e32 v10, v10, v64
	v_add_f32_e32 v54, v54, v59
	v_add_f32_e32 v55, v55, v69
	v_add_f32_e32 v56, v56, v73
	v_add_f32_e32 v57, v57, v77
	v_add_f32_e32 v58, v58, v81
	v_add_f32_e32 v59, v62, v85
	v_add_f32_e32 v50, v50, v52
	v_add_f32_e32 v10, v10, v65
	v_add_f32_e32 v51, v54, v60
	v_add_f32_e32 v54, v55, v70
	v_add_f32_e32 v55, v56, v74
	v_add_f32_e32 v56, v57, v78
	v_add_f32_e32 v57, v58, v82
	v_add_f32_e32 v58, v59, v86
	v_add_f32_e32 v50, v50, v53
	v_mul_f32_e32 v4, v4, v10
	v_add_f32_e32 v10, v51, v61
	v_add_f32_e32 v51, v54, v71
	v_add_f32_e32 v52, v55, v75
	v_add_f32_e32 v54, v56, v79
	v_add_f32_e32 v55, v57, v83
	v_add_f32_e32 v56, v58, v87
	v_mul_f32_e32 v3, v3, v50
	v_mul_f32_e32 v5, v5, v10
	v_mul_f32_e32 v6, v6, v51
	v_mul_f32_e32 v7, v7, v52
	v_mul_f32_e32 v10, v0, v54
	v_mul_f32_e32 v51, v1, v55
	v_mul_f32_e32 v52, v2, v56
	v_cvt_pk_bf16_f32 v0, v4, v5
	v_cvt_pk_bf16_f32 v1, v6, v7
	v_cvt_pk_bf16_f32 v2, v10, v51
	v_cvt_pk_bf16_f32 v3, v52, v3
	global_store_dwordx4 v[66:67], v[0:3], off
	s_andn2_b64 exec, exec, s[10:11]
	s_cbranch_execnz .LBB0_25
; __device__ __forceinline__ unsigned cvt_pk_bf16(float lo, float hi) { unsigned r; asm volatile("v_cvt_pk_bf16_f32 %0, %1, %2" : "=v"(r) : "v"(lo), "v"(hi)); return r; }
;     const long total = (long)(K / 8) * Ndst;
; #pragma unroll 4
;     for (long it = gtid; it < total; it += gsz) {
;         const int n = (int)(it % Ndst), k8 = (int)(it / Ndst);
;         int sc = n;
;         if (MODE == 1) { if (n < 3584) sc = n; else sc = n + 16; }
;         u32x4 w = {0u, 0u, 0u, 0u};
;         if (sc >= 0) {
;             const float* s = src + (size_t)(k8 * 8) * Nsrc + sc;
;             float v0 = s[0], v1 = s[(size_t)Nsrc], v2 = s[(size_t)2 * Nsrc], v3 = s[(size_t)3 * Nsrc], v4 = s[(size_t)4 * Nsrc], v5 = s[(size_t)5 * Nsrc], v6 = s[(size_t)6 * Nsrc], v7 = s[(size_t)7 * Nsrc];
;             if (gain) { const f32x4 g0 = *(const f32x4*)(gain + k8 * 8), g1 = *(const f32x4*)(gain + k8 * 8 + 4); v0 *= g0[0]; v1 *= g0[1]; v2 *= g0[2]; v3 *= g0[3]; v4 *= g1[0]; v5 *= g1[1]; v6 *= g1[2]; v7 *= g1[3]; }
;             w.x = cvt_pk_bf16(v0 * wscale, v1 * wscale); w.y = cvt_pk_bf16(v2 * wscale, v3 * wscale); w.z = cvt_pk_bf16(v4 * wscale, v5 * wscale); w.w = cvt_pk_bf16(v6 * wscale, v7 * wscale);
;         }
;         *(u32x4*)(dst + (size_t)n * K + k8 * 8) = w;
;     }
; }
; __device__ __forceinline__ void phase0(const Params& p) {
;     ...
;     transpose_w<0>(p.in[13], 2048, 1024, (bf16_t*)(ws + WS_WOUTE), 1024, nullptr, gtid, gsz);
.LBB0_26:
	s_or_b64 exec, exec, s[0:1]
	s_cmpk_eq_i32 s94, 0x100
	s_cbranch_scc1 .LBB0_37
	s_mov_b64 s[0:1], 0x40000
	v_cmp_gt_u64_e32 vcc, s[0:1], v[8:9]
	s_and_saveexec_b64 s[0:1], vcc
	v_readlane_b32 s12, v250, 20
	v_readlane_b32 s16, v250, 24
	v_readlane_b32 s17, v250, 25
	v_readlane_b32 s18, v250, 26
	v_readlane_b32 s19, v250, 27
	v_readlane_b32 s20, v250, 28
	v_readlane_b32 s21, v250, 29
	v_readlane_b32 s22, v250, 30
	v_readlane_b32 s23, v250, 31
	v_readlane_b32 s24, v250, 32
	v_readlane_b32 s25, v250, 33
	v_readlane_b32 s26, v250, 34
	v_readlane_b32 s27, v250, 35
	v_readlane_b32 s13, v250, 21
	v_readlane_b32 s14, v250, 22
	v_readlane_b32 s15, v250, 23
	s_cbranch_execz .LBB0_29
	s_mov_b64 s[12:13], s[16:17]
	s_mov_b64 s[14:15], s[18:19]
	s_add_u32 s10, s44, 0xc00000
	s_mov_b64 s[16:17], s[20:21]
	s_mov_b64 s[18:19], s[22:23]
	s_addc_u32 s11, s45, 0
	s_mov_b64 s[12:13], 0
	v_mov_b32_e32 v1, 0
	s_mov_b64 s[14:15], 0x3ffff
	v_mov_b64_e32 v[2:3], v[8:9]
	s_mov_b64 s[20:21], s[24:25]
	s_mov_b64 s[22:23], s[26:27]
.LBB0_28:
	v_lshrrev_b32_e32 v0, 7, v2
	v_and_b32_e32 v0, 0x1fffff8, v0
	v_and_b32_e32 v14, 0x3ff, v2
	v_lshlrev_b64 v[6:7], 12, v[0:1]
	v_mov_b32_e32 v5, v1
	v_lshlrev_b32_e32 v4, 2, v14
	v_lshl_add_u64 v[6:7], s[18:19], 0, v[6:7]
	v_lshl_add_u64 v[4:5], v[6:7], 0, v[4:5]
	v_add_co_u32_e32 v6, vcc, 0x1000, v4
	v_lshl_add_u64 v[2:3], v[2:3], 0, s[6:7]
	s_nop 0
	v_addc_co_u32_e32 v7, vcc, 0, v5, vcc
	v_add_co_u32_e32 v10, vcc, 0x3000, v4
	global_load_dword v15, v[6:7], off nt
	s_nop 0
	v_addc_co_u32_e32 v11, vcc, 0, v5, vcc
	v_add_co_u32_e32 v6, vcc, 0x2000, v4
	v_lshlrev_b32_e32 v0, 1, v0
	s_nop 0
	v_addc_co_u32_e32 v7, vcc, 0, v5, vcc
	v_add_co_u32_e32 v12, vcc, 0x5000, v4
	global_load_dword v16, v[10:11], off nt
	global_load_dword v17, v[6:7], off nt
	v_addc_co_u32_e32 v13, vcc, 0, v5, vcc
	v_add_co_u32_e32 v6, vcc, 0x4000, v4
	s_nop 1
	v_addc_co_u32_e32 v7, vcc, 0, v5, vcc
	v_add_co_u32_e32 v10, vcc, 0x7000, v4
	global_load_dword v12, v[12:13], off nt
	s_nop 0
	global_load_dword v13, v[6:7], off nt
	v_addc_co_u32_e32 v11, vcc, 0, v5, vcc
	v_add_co_u32_e32 v6, vcc, 0x6000, v4
	s_nop 1
	v_addc_co_u32_e32 v7, vcc, 0, v5, vcc
	global_load_dword v18, v[10:11], off nt
	s_nop 0
	global_load_dword v7, v[6:7], off nt
	s_nop 0
	global_load_dword v6, v[4:5], off nt
	v_mov_b32_e32 v5, v1
	v_lshlrev_b32_e32 v4, 12, v14
	v_cmp_lt_u64_e32 vcc, s[14:15], v[2:3]
	v_lshl_add_u64 v[4:5], s[10:11], 0, v[4:5]
	s_or_b64 s[12:13], vcc, s[12:13]
	v_lshl_add_u64 v[10:11], v[4:5], 0, v[0:1]
	s_waitcnt vmcnt(0)
	v_cvt_pk_bf16_f32 v4, v6, v15
	v_cvt_pk_bf16_f32 v5, v17, v16
	v_cvt_pk_bf16_f32 v6, v13, v12
	v_cvt_pk_bf16_f32 v7, v7, v18
	global_store_dwordx4 v[10:11], v[4:7], off
	s_andn2_b64 exec, exec, s[12:13]
	s_cbranch_execnz .LBB0_28

; __device__ __forceinline__ unsigned cvt_pk_bf16(float lo, float hi) { unsigned r; asm volatile("v_cvt_pk_bf16_f32 %0, %1, %2" : "=v"(r) : "v"(lo), "v"(hi)); return r; }
;     const long total = (long)(K / 8) * Ndst;
; #pragma unroll 4
;     for (long it = gtid; it < total; it += gsz) {
;         const int n = (int)(it % Ndst), k8 = (int)(it / Ndst);
;         int sc = n;
;         if (MODE == 1) { if (n < 3584) sc = n; else sc = n + 16; }
;         u32x4 w = {0u, 0u, 0u, 0u};
;         if (sc >= 0) {
;             const float* s = src + (size_t)(k8 * 8) * Nsrc + sc;
;             float v0 = s[0], v1 = s[(size_t)Nsrc], v2 = s[(size_t)2 * Nsrc], v3 = s[(size_t)3 * Nsrc], v4 = s[(size_t)4 * Nsrc], v5 = s[(size_t)5 * Nsrc], v6 = s[(size_t)6 * Nsrc], v7 = s[(size_t)7 * Nsrc];
;             if (gain) { const f32x4 g0 = *(const f32x4*)(gain + k8 * 8), g1 = *(const f32x4*)(gain + k8 * 8 + 4); v0 *= g0[0]; v1 *= g0[1]; v2 *= g0[2]; v3 *= g0[3]; v4 *= g1[0]; v5 *= g1[1]; v6 *= g1[2]; v7 *= g1[3]; }
;             w.x = cvt_pk_bf16(v0 * wscale, v1 * wscale); w.y = cvt_pk_bf16(v2 * wscale, v3 * wscale); w.z = cvt_pk_bf16(v4 * wscale, v5 * wscale); w.w = cvt_pk_bf16(v6 * wscale, v7 * wscale);
;         }
;         *(u32x4*)(dst + (size_t)n * K + k8 * 8) = w;
;     }
; }
; __device__ __forceinline__ void phase0(const Params& p) {
;     ...
;     transpose_w<0>(p.in[15], 1024, 3072, (bf16_t*)(ws + WS_WINO), 3072, p.in[14], gtid, gsz);
.LBB0_32:
	v_mul_hi_u32 v0, v4, s18
	v_lshrrev_b32_e32 v6, 11, v0
	v_mul_u32_u24_e32 v0, 0xc00, v6
	v_lshlrev_b32_e32 v16, 3, v6
	v_sub_u32_e32 v0, v4, v0
	v_mad_u64_u32 v[6:7], s[20:21], v16, s19, v[2:3]
	v_lshl_add_u64 v[6:7], v[0:1], 2, v[6:7]
	v_add_co_u32_e32 v10, vcc, 0x3000, v6
	s_nop 1
	v_addc_co_u32_e32 v11, vcc, 0, v7, vcc
	v_add_co_u32_e32 v12, vcc, 0x6000, v6
	s_nop 1
	v_addc_co_u32_e32 v13, vcc, 0, v7, vcc
	v_add_co_u32_e32 v14, vcc, 0x9000, v6
	s_nop 1
	v_addc_co_u32_e32 v15, vcc, 0, v7, vcc
	v_add_co_u32_e32 v18, vcc, 0xc000, v6
	s_nop 1
	v_addc_co_u32_e32 v19, vcc, 0, v7, vcc
	v_add_co_u32_e32 v20, vcc, 0xf000, v6
	s_nop 1
	v_addc_co_u32_e32 v21, vcc, 0, v7, vcc
	v_add_co_u32_e32 v22, vcc, 0x12000, v6
	s_nop 1
	v_addc_co_u32_e32 v23, vcc, 0, v7, vcc
	v_add_co_u32_e32 v24, vcc, 0x15000, v6
	s_nop 1
	v_addc_co_u32_e32 v25, vcc, 0, v7, vcc
	global_load_dword v6, v[6:7], off nt
	s_nop 0
	global_load_dword v7, v[10:11], off nt
	s_nop 0
	global_load_dword v10, v[12:13], off nt
	global_load_dword v11, v[14:15], off nt
	s_nop 0
	global_load_dword v14, v[18:19], off nt
	global_load_dword v15, v[20:21], off nt
	global_load_dword v12, v[22:23], off nt
	global_load_dword v13, v[24:25], off nt
	s_and_b64 vcc, exec, s[0:1]
	s_cbranch_vccnz .LBB0_31
	v_readlane_b32 s48, v250, 20
	v_lshlrev_b32_e32 v17, 2, v16
	v_readlane_b32 s60, v250, 32
	v_readlane_b32 s61, v250, 33
	s_nop 4
	global_load_dwordx4 v[18:21], v17, s[60:61]
	global_load_dwordx4 v[22:25], v17, s[60:61] offset:16
	v_readlane_b32 s49, v250, 21
	v_readlane_b32 s50, v250, 22
	v_readlane_b32 s51, v250, 23
	v_readlane_b32 s52, v250, 24
	v_readlane_b32 s53, v250, 25
	v_readlane_b32 s54, v250, 26
	v_readlane_b32 s55, v250, 27
	v_readlane_b32 s56, v250, 28
	v_readlane_b32 s57, v250, 29
	v_readlane_b32 s58, v250, 30
	v_readlane_b32 s59, v250, 31
	v_readlane_b32 s62, v250, 34
	v_readlane_b32 s63, v250, 35
	s_waitcnt vmcnt(1)
	v_pk_mul_f32 v[6:7], v[6:7], v[18:19]
	v_pk_mul_f32 v[10:11], v[10:11], v[20:21]
	s_waitcnt vmcnt(0)
	v_pk_mul_f32 v[14:15], v[14:15], v[22:23]
	v_pk_mul_f32 v[12:13], v[12:13], v[24:25]
	s_branch .LBB0_31

; __device__ __forceinline__ unsigned cvt_pk_bf16(float lo, float hi) { unsigned r; asm volatile("v_cvt_pk_bf16_f32 %0, %1, %2" : "=v"(r) : "v"(lo), "v"(hi)); return r; }
;     const long total = (long)(K / 8) * Ndst;
; #pragma unroll 4
;     for (long it = gtid; it < total; it += gsz) {
;         const int n = (int)(it % Ndst), k8 = (int)(it / Ndst);
;         int sc = n;
;         if (MODE == 1) { if (n < 3584) sc = n; else sc = n + 16; }
;         u32x4 w = {0u, 0u, 0u, 0u};
;         if (sc >= 0) {
;             const float* s = src + (size_t)(k8 * 8) * Nsrc + sc;
;             float v0 = s[0], v1 = s[(size_t)Nsrc], v2 = s[(size_t)2 * Nsrc], v3 = s[(size_t)3 * Nsrc], v4 = s[(size_t)4 * Nsrc], v5 = s[(size_t)5 * Nsrc], v6 = s[(size_t)6 * Nsrc], v7 = s[(size_t)7 * Nsrc];
;             if (gain) { const f32x4 g0 = *(const f32x4*)(gain + k8 * 8), g1 = *(const f32x4*)(gain + k8 * 8 + 4); v0 *= g0[0]; v1 *= g0[1]; v2 *= g0[2]; v3 *= g0[3]; v4 *= g1[0]; v5 *= g1[1]; v6 *= g1[2]; v7 *= g1[3]; }
;             w.x = cvt_pk_bf16(v0 * wscale, v1 * wscale); w.y = cvt_pk_bf16(v2 * wscale, v3 * wscale); w.z = cvt_pk_bf16(v4 * wscale, v5 * wscale); w.w = cvt_pk_bf16(v6 * wscale, v7 * wscale);
;         }
;         *(u32x4*)(dst + (size_t)n * K + k8 * 8) = w;
;     }
; }
; __device__ __forceinline__ void phase0(const Params& p) {
;     ...
;     transpose_w<0>(p.in[23], 1536, 1024, (bf16_t*)(ws + WS_WOUTO), 1024, nullptr, gtid, gsz);
.LBB0_36:
	v_lshrrev_b32_e32 v0, 7, v4
	v_and_b32_e32 v0, 0x1fffff8, v0
	v_and_b32_e32 v16, 0x3ff, v4
	v_lshlrev_b64 v[10:11], 12, v[0:1]
	v_mov_b32_e32 v7, v1
	v_lshlrev_b32_e32 v6, 2, v16
	v_lshl_add_u64 v[10:11], s[26:27], 0, v[10:11]
	v_lshl_add_u64 v[6:7], v[10:11], 0, v[6:7]
	v_add_co_u32_e32 v10, vcc, 0x1000, v6
	v_lshl_add_u64 v[4:5], v[4:5], 0, s[6:7]
	s_nop 0
	v_addc_co_u32_e32 v11, vcc, 0, v7, vcc
	v_add_co_u32_e32 v12, vcc, 0x3000, v6
	global_load_dword v17, v[10:11], off nt
	s_nop 0
	v_addc_co_u32_e32 v13, vcc, 0, v7, vcc
	v_add_co_u32_e32 v10, vcc, 0x2000, v6
	v_lshlrev_b32_e32 v0, 1, v0
	s_nop 0
	v_addc_co_u32_e32 v11, vcc, 0, v7, vcc
	v_add_co_u32_e32 v14, vcc, 0x5000, v6
	global_load_dword v18, v[12:13], off nt
	global_load_dword v19, v[10:11], off nt
	v_addc_co_u32_e32 v15, vcc, 0, v7, vcc
	v_add_co_u32_e32 v10, vcc, 0x4000, v6
	s_nop 1
	v_addc_co_u32_e32 v11, vcc, 0, v7, vcc
	v_add_co_u32_e32 v12, vcc, 0x7000, v6
	global_load_dword v14, v[14:15], off nt
	s_nop 0
	global_load_dword v15, v[10:11], off nt
	v_addc_co_u32_e32 v13, vcc, 0, v7, vcc
	v_add_co_u32_e32 v10, vcc, 0x6000, v6
	s_nop 1
	v_addc_co_u32_e32 v11, vcc, 0, v7, vcc
	global_load_dword v13, v[12:13], off nt
	s_nop 0
	global_load_dword v20, v[10:11], off nt
	s_nop 0
	global_load_dword v10, v[6:7], off nt
	v_mad_u64_u32 v[6:7], s[16:17], v16, s14, v[2:3]
	v_cmp_lt_u64_e32 vcc, s[12:13], v[4:5]
	s_or_b64 s[10:11], vcc, s[10:11]
	v_lshl_add_u64 v[6:7], v[6:7], 0, v[0:1]
	s_waitcnt vmcnt(0)
	v_cvt_pk_bf16_f32 v10, v10, v17
	v_cvt_pk_bf16_f32 v11, v19, v18
	v_cvt_pk_bf16_f32 v12, v15, v14
	v_cvt_pk_bf16_f32 v13, v20, v13
	global_store_dwordx4 v[6:7], v[10:13], off
	s_andn2_b64 exec, exec, s[10:11]
	s_cbranch_execnz .LBB0_36

; __device__ __forceinline__ unsigned cvt_pk_bf16(float lo, float hi) { unsigned r; asm volatile("v_cvt_pk_bf16_f32 %0, %1, %2" : "=v"(r) : "v"(lo), "v"(hi)); return r; }
;     const long total = (long)(K / 8) * Ndst;
; #pragma unroll 4
;     for (long it = gtid; it < total; it += gsz) {
;         const int n = (int)(it % Ndst), k8 = (int)(it / Ndst);
;         int sc = n;
;         if (MODE == 1) { if (n < 3584) sc = n; else sc = n + 16; }
;         u32x4 w = {0u, 0u, 0u, 0u};
;         if (sc >= 0) {
;             const float* s = src + (size_t)(k8 * 8) * Nsrc + sc;
;             float v0 = s[0], v1 = s[(size_t)Nsrc], v2 = s[(size_t)2 * Nsrc], v3 = s[(size_t)3 * Nsrc], v4 = s[(size_t)4 * Nsrc], v5 = s[(size_t)5 * Nsrc], v6 = s[(size_t)6 * Nsrc], v7 = s[(size_t)7 * Nsrc];
;             if (gain) { const f32x4 g0 = *(const f32x4*)(gain + k8 * 8), g1 = *(const f32x4*)(gain + k8 * 8 + 4); v0 *= g0[0]; v1 *= g0[1]; v2 *= g0[2]; v3 *= g0[3]; v4 *= g1[0]; v5 *= g1[1]; v6 *= g1[2]; v7 *= g1[3]; }
;             w.x = cvt_pk_bf16(v0 * wscale, v1 * wscale); w.y = cvt_pk_bf16(v2 * wscale, v3 * wscale); w.z = cvt_pk_bf16(v4 * wscale, v5 * wscale); w.w = cvt_pk_bf16(v6 * wscale, v7 * wscale);
;         }
;         *(u32x4*)(dst + (size_t)n * K + k8 * 8) = w;
;     }
; }
; __device__ __forceinline__ void phase0(const Params& p) {
;     ...
;     for (int nb = 0; nb < 8; ++nb) {
;         transpose_w<0>(p.in[18] + nb * 192 * 192, 192, 192, (bf16_t*)(ws + WS_WA) + nb * 192 * 192, 192, nullptr, gtid, gsz, 1.4426950408889634f);
;         transpose_w<0>(p.in[20] + nb * 192 * 192, 192, 192, (bf16_t*)(ws + WS_WI) + nb * 192 * 192, 192, nullptr, gtid, gsz, 1.4426950408889634f);
;     }
.LBB0_41:
	v_mul_u32_u24_sdwa v0, v6, s26 dst_sel:DWORD dst_unused:UNUSED_PAD src0_sel:WORD_0 src1_sel:DWORD
	v_lshrrev_b32_e32 v0, 23, v0
	v_mul_lo_u16_e32 v12, 0xc0, v0
	v_lshlrev_b16_e32 v13, 3, v0
	v_sub_u16_e32 v12, v6, v12
	v_mad_u64_u32 v[10:11], s[0:1], v13, s27, v[2:3]
	v_lshlrev_b32_e32 v0, 2, v12
	v_lshl_add_u64 v[10:11], v[10:11], 0, v[0:1]
	global_load_dword v16, v[10:11], off nt
	global_load_dword v17, v[10:11], off offset:768 nt
	global_load_dword v18, v[10:11], off offset:1536 nt
	global_load_dword v19, v[10:11], off offset:2304 nt
	global_load_dword v20, v[10:11], off offset:3072 nt
	global_load_dword v21, v[10:11], off offset:3840 nt
	v_add_co_u32_e64 v10, s[0:1], s28, v10
	v_lshl_add_u64 v[6:7], v[6:7], 0, s[6:7]
	s_nop 0
	v_addc_co_u32_e64 v11, s[0:1], 0, v11, s[0:1]
	global_load_dword v22, v[10:11], off offset:512 nt
	global_load_dword v23, v[10:11], off offset:1280 nt
	v_mad_u64_u32 v[10:11], s[0:1], v12, s29, v[4:5]
	v_lshlrev_b32_e32 v0, 1, v13
	v_cmp_lt_u64_e64 s[0:1], s[10:11], v[6:7]
	v_lshl_add_u64 v[14:15], v[10:11], 0, v[0:1]
	s_or_b64 s[20:21], s[0:1], s[20:21]
	s_waitcnt vmcnt(7)
	v_mul_f32_e32 v0, 0x3fb8aa3b, v16
	s_waitcnt vmcnt(6)
	v_mul_f32_e32 v10, 0x3fb8aa3b, v17
	s_waitcnt vmcnt(5)
	v_mul_f32_e32 v11, 0x3fb8aa3b, v18
	s_waitcnt vmcnt(4)
	v_mul_f32_e32 v12, 0x3fb8aa3b, v19
	s_waitcnt vmcnt(3)
	v_mul_f32_e32 v13, 0x3fb8aa3b, v20
	s_waitcnt vmcnt(2)
	v_mul_f32_e32 v16, 0x3fb8aa3b, v21
	v_cvt_pk_bf16_f32 v10, v0, v10
	v_cvt_pk_bf16_f32 v11, v11, v12
	v_cvt_pk_bf16_f32 v12, v13, v16
	s_waitcnt vmcnt(1)
	v_mul_f32_e32 v0, 0x3fb8aa3b, v22
	s_waitcnt vmcnt(0)
	v_mul_f32_e32 v13, 0x3fb8aa3b, v23
	v_cvt_pk_bf16_f32 v13, v0, v13
	global_store_dwordx4 v[14:15], v[10:13], off
	s_andn2_b64 exec, exec, s[20:21]
	s_cbranch_execnz .LBB0_41
	s_or_b64 exec, exec, s[20:21]
	v_readlane_b32 s48, v250, 36
	v_readlane_b32 s56, v250, 44
	v_readlane_b32 s57, v250, 45
	s_add_u32 s0, s56, s16
	s_addc_u32 s1, s57, s17
	s_add_u32 s18, s24, s18
	s_addc_u32 s19, s25, s19
	s_mov_b64 s[16:17], 0
	v_mov_b64_e32 v[2:3], s[0:1]
	v_mov_b64_e32 v[4:5], s[18:19]
	v_mov_b64_e32 v[6:7], v[8:9]
	v_readlane_b32 s49, v250, 37
	v_readlane_b32 s50, v250, 38
	v_readlane_b32 s51, v250, 39
	v_readlane_b32 s52, v250, 40
	v_readlane_b32 s53, v250, 41
	v_readlane_b32 s54, v250, 42
	v_readlane_b32 s55, v250, 43
	v_readlane_b32 s58, v250, 46
	v_readlane_b32 s59, v250, 47
	v_readlane_b32 s60, v250, 48
	v_readlane_b32 s61, v250, 49
	v_readlane_b32 s62, v250, 50
	v_readlane_b32 s63, v250, 51
.LBB0_43:
	v_mul_u32_u24_sdwa v0, v6, s26 dst_sel:DWORD dst_unused:UNUSED_PAD src0_sel:WORD_0 src1_sel:DWORD
	v_lshrrev_b32_e32 v0, 23, v0
	v_mul_lo_u16_e32 v12, 0xc0, v0
	v_lshlrev_b16_e32 v13, 3, v0
	v_sub_u16_e32 v12, v6, v12
	v_mad_u64_u32 v[10:11], s[0:1], v13, s27, v[2:3]
	v_lshlrev_b32_e32 v0, 2, v12
	v_lshl_add_u64 v[10:11], v[10:11], 0, v[0:1]
	global_load_dword v16, v[10:11], off nt
	global_load_dword v17, v[10:11], off offset:768 nt
	global_load_dword v18, v[10:11], off offset:1536 nt
	global_load_dword v19, v[10:11], off offset:2304 nt
	global_load_dword v20, v[10:11], off offset:3072 nt
	global_load_dword v21, v[10:11], off offset:3840 nt
	v_add_co_u32_e64 v10, s[0:1], s28, v10
	v_lshl_add_u64 v[6:7], v[6:7], 0, s[6:7]
	s_nop 0
	v_addc_co_u32_e64 v11, s[0:1], 0, v11, s[0:1]
	global_load_dword v22, v[10:11], off offset:512 nt
	global_load_dword v23, v[10:11], off offset:1280 nt
	v_mad_u64_u32 v[10:11], s[0:1], v12, s29, v[4:5]
	v_lshlrev_b32_e32 v0, 1, v13
	v_cmp_lt_u64_e64 s[0:1], s[10:11], v[6:7]
	v_lshl_add_u64 v[14:15], v[10:11], 0, v[0:1]
	s_or_b64 s[16:17], s[0:1], s[16:17]
	s_waitcnt vmcnt(7)
	v_mul_f32_e32 v0, 0x3fb8aa3b, v16
	s_waitcnt vmcnt(6)
	v_mul_f32_e32 v10, 0x3fb8aa3b, v17
	s_waitcnt vmcnt(5)
	v_mul_f32_e32 v11, 0x3fb8aa3b, v18
	s_waitcnt vmcnt(4)
	v_mul_f32_e32 v12, 0x3fb8aa3b, v19
	s_waitcnt vmcnt(3)
	v_mul_f32_e32 v13, 0x3fb8aa3b, v20
	s_waitcnt vmcnt(2)
	v_mul_f32_e32 v16, 0x3fb8aa3b, v21
	v_cvt_pk_bf16_f32 v10, v0, v10
	v_cvt_pk_bf16_f32 v11, v11, v12
	v_cvt_pk_bf16_f32 v12, v13, v16
	s_waitcnt vmcnt(1)
	v_mul_f32_e32 v0, 0x3fb8aa3b, v22
	s_waitcnt vmcnt(0)
	v_mul_f32_e32 v13, 0x3fb8aa3b, v23
	v_cvt_pk_bf16_f32 v13, v0, v13
	global_store_dwordx4 v[14:15], v[10:13], off
	s_andn2_b64 exec, exec, s[16:17]
	s_cbranch_execnz .LBB0_43
	s_or_b64 exec, exec, s[16:17]
	s_branch .LBB0_38
.Lwawi_fast:
	s_and_b32 s0, s2, 15
	s_cmp_gt_u32 s0, 8
	s_cbranch_scc1 .LBB0_45
	s_lshl_b32 s0, s0, 9
	v_add_u32_e32 v6, s0, v136
	s_lshr_b32 s12, s2, 5
	s_mul_i32 s12, s12, 0x9000
	v_readlane_b32 s52, v250, 40
	v_readlane_b32 s53, v250, 41
	v_readlane_b32 s56, v250, 44
	v_readlane_b32 s57, v250, 45
	s_nop 1
	s_bitcmp1_b32 s2, 4
	s_cselect_b32 s0, s56, s52
	s_cselect_b32 s1, s57, s53
	s_cselect_b32 s14, 0x90000, 0
	s_add_i32 s14, s14, 0x1900000
	s_lshl_b64 s[16:17], s[12:13], 2
	s_add_u32 s0, s0, s16
	s_addc_u32 s1, s1, s17
	s_lshl_b32 s18, s12, 1
	s_add_u32 s34, s44, s14
	s_addc_u32 s35, s45, 0
	s_add_u32 s34, s34, s18
	s_addc_u32 s35, s35, 0
	v_mov_b64_e32 v[2:3], s[0:1]
	v_mov_b64_e32 v[4:5], s[34:35]
	v_mul_u32_u24_sdwa v0, v6, s26 dst_sel:DWORD dst_unused:UNUSED_PAD src0_sel:WORD_0 src1_sel:DWORD
	v_lshrrev_b32_e32 v0, 23, v0
	v_mul_lo_u16_e32 v12, 0xc0, v0
	v_lshlrev_b16_e32 v13, 3, v0
	v_sub_u16_e32 v12, v6, v12
	v_mad_u64_u32 v[10:11], s[0:1], v13, s27, v[2:3]
	v_lshlrev_b32_e32 v0, 2, v12
	v_lshl_add_u64 v[10:11], v[10:11], 0, v[0:1]
	global_load_dword v16, v[10:11], off nt
	global_load_dword v17, v[10:11], off offset:768 nt
	global_load_dword v18, v[10:11], off offset:1536 nt
	global_load_dword v19, v[10:11], off offset:2304 nt
	global_load_dword v20, v[10:11], off offset:3072 nt
	global_load_dword v21, v[10:11], off offset:3840 nt
	v_add_co_u32_e64 v10, s[0:1], s28, v10
	s_nop 1
	v_addc_co_u32_e64 v11, s[0:1], 0, v11, s[0:1]
	global_load_dword v22, v[10:11], off offset:512 nt
	global_load_dword v23, v[10:11], off offset:1280 nt
	v_mad_u64_u32 v[10:11], s[0:1], v12, s29, v[4:5]
	v_lshlrev_b32_e32 v0, 1, v13
	v_lshl_add_u64 v[14:15], v[10:11], 0, v[0:1]
	s_waitcnt vmcnt(7)
	v_mul_f32_e32 v0, 0x3fb8aa3b, v16
	s_waitcnt vmcnt(6)
	v_mul_f32_e32 v10, 0x3fb8aa3b, v17
	s_waitcnt vmcnt(5)
	v_mul_f32_e32 v11, 0x3fb8aa3b, v18
	s_waitcnt vmcnt(4)
	v_mul_f32_e32 v12, 0x3fb8aa3b, v19
	s_waitcnt vmcnt(3)
	v_mul_f32_e32 v13, 0x3fb8aa3b, v20
	s_waitcnt vmcnt(2)
	v_mul_f32_e32 v16, 0x3fb8aa3b, v21
	v_cvt_pk_bf16_f32 v10, v0, v10
	v_cvt_pk_bf16_f32 v11, v11, v12
	v_cvt_pk_bf16_f32 v12, v13, v16
	s_waitcnt vmcnt(1)
	v_mul_f32_e32 v0, 0x3fb8aa3b, v22
	s_waitcnt vmcnt(0)
	v_mul_f32_e32 v13, 0x3fb8aa3b, v23
	v_cvt_pk_bf16_f32 v13, v0, v13
	global_store_dwordx4 v[14:15], v[10:13], off

; __device__ __forceinline__ unsigned cvt_pk_bf16(float lo, float hi) { unsigned r; asm volatile("v_cvt_pk_bf16_f32 %0, %1, %2" : "=v"(r) : "v"(lo), "v"(hi)); return r; }
;     const long total = (long)(K / 8) * Ndst;
; #pragma unroll 4
;     for (long it = gtid; it < total; it += gsz) {
;         const int n = (int)(it % Ndst), k8 = (int)(it / Ndst);
;         int sc = n;
;         if (MODE == 1) { if (n < 3584) sc = n; else sc = n + 16; }
;         u32x4 w = {0u, 0u, 0u, 0u};
;         if (sc >= 0) {
;             const float* s = src + (size_t)(k8 * 8) * Nsrc + sc;
;             float v0 = s[0], v1 = s[(size_t)Nsrc], v2 = s[(size_t)2 * Nsrc], v3 = s[(size_t)3 * Nsrc], v4 = s[(size_t)4 * Nsrc], v5 = s[(size_t)5 * Nsrc], v6 = s[(size_t)6 * Nsrc], v7 = s[(size_t)7 * Nsrc];
;             if (gain) { const f32x4 g0 = *(const f32x4*)(gain + k8 * 8), g1 = *(const f32x4*)(gain + k8 * 8 + 4); v0 *= g0[0]; v1 *= g0[1]; v2 *= g0[2]; v3 *= g0[3]; v4 *= g1[0]; v5 *= g1[1]; v6 *= g1[2]; v7 *= g1[3]; }
;             w.x = cvt_pk_bf16(v0 * wscale, v1 * wscale); w.y = cvt_pk_bf16(v2 * wscale, v3 * wscale); w.z = cvt_pk_bf16(v4 * wscale, v5 * wscale); w.w = cvt_pk_bf16(v6 * wscale, v7 * wscale);
;         }
;         *(u32x4*)(dst + (size_t)n * K + k8 * 8) = w;
;     }
; }
; __device__ __forceinline__ void phase0(const Params& p) {
;     ...
;     transpose_w<0>(p.in[13], 2048, 1024, (bf16_t*)(ws + WS_WOUTE), 1024, nullptr, gtid, gsz);
;     transpose_w<0>(p.in[15], 1024, 3072, (bf16_t*)(ws + WS_WINO), 3072, p.in[14], gtid, gsz);
;     transpose_w<0>(p.in[23], 1536, 1024, (bf16_t*)(ws + WS_WOUTO), 1024, nullptr, gtid, gsz);
.LBB0_238:
	s_waitcnt vmcnt(0)
	v_readlane_b32 s94, v250, 54
	v_readlane_b32 s92, v250, 52
	v_readlane_b32 s95, v250, 55
	v_readlane_b32 s93, v250, 53
	s_barrier
	s_cmpk_lg_i32 s94, 0x100
	s_cbranch_scc1 .Ldw_done
	s_cmpk_lt_u32 s2, 0xc0
	s_cbranch_scc1 .Ldw_done
	v_writelane_b32 v251, s0, 0
	v_writelane_b32 v251, s10, 1
	v_writelane_b32 v251, s11, 2
	v_writelane_b32 v251, s12, 3
	v_writelane_b32 v251, s13, 4
	v_writelane_b32 v251, s14, 5
	v_writelane_b32 v251, s15, 6
	v_writelane_b32 v251, s16, 7
	v_writelane_b32 v251, s17, 8
	v_writelane_b32 v251, s18, 9
	v_writelane_b32 v251, s19, 10
	v_writelane_b32 v251, s20, 11
	v_writelane_b32 v251, s21, 12
	v_writelane_b32 v251, s22, 13
	v_writelane_b32 v251, s23, 14
	v_writelane_b32 v251, s24, 15
	v_writelane_b32 v251, s25, 16
	v_writelane_b32 v251, s26, 17
	v_writelane_b32 v251, s48, 18
	v_writelane_b32 v251, s49, 19
	v_writelane_b32 v251, s50, 20
	v_writelane_b32 v251, s51, 21
	v_writelane_b32 v251, s52, 22
	v_writelane_b32 v251, s53, 23
	v_writelane_b32 v251, s54, 24
	v_writelane_b32 v251, s55, 25
	v_writelane_b32 v251, s56, 26
	v_writelane_b32 v251, s57, 27
	v_writelane_b32 v251, s58, 28
	v_writelane_b32 v251, s59, 29
	v_writelane_b32 v251, s60, 30
	v_writelane_b32 v251, s61, 31
	v_writelane_b32 v251, s62, 32
	v_writelane_b32 v251, s63, 33
	v_lshrrev_b32_e32 v0, 6, v136
	s_sub_u32 s10, s2, 0xc0
	s_nop 0
	v_readfirstlane_b32 s0, v0
	v_and_b32_e32 v0, 63, v136
	s_lshl_b32 s10, s10, 3
	v_lshlrev_b32_e32 v2, 2, v0
	s_add_u32 s10, s10, s0
.Ldw_loop:
	s_cmpk_ge_u32 s10, 0xd00
	s_cbranch_scc1 .Ldw_end
	s_cmpk_lt_u32 s10, 0x400
	s_cbranch_scc1 .Ldw_m0
	s_cmpk_lt_u32 s10, 0xa00
	s_cbranch_scc1 .Ldw_m1
	s_sub_u32 s11, s10, 0xa00
	s_and_b32 s18, s11, 15
	s_lshr_b32 s19, s11, 4
	v_readlane_b32 s12, v250, 50
	v_readlane_b32 s13, v250, 51
	s_movk_i32 s14, 0x1000
	s_movk_i32 s15, 0xc00
	s_mov_b32 s20, 0x1600000
	s_mov_b32 s26, 0
	s_branch .Ldw_go
.Ldw_m0:
	s_and_b32 s18, s10, 15
	s_lshr_b32 s19, s10, 4
	v_readlane_b32 s12, v250, 30
	v_readlane_b32 s13, v250, 31
	s_movk_i32 s14, 0x1000
	s_movk_i32 s15, 0x1000
	s_mov_b32 s20, 0xc00000
	s_mov_b32 s26, 0
	s_branch .Ldw_go
.Ldw_m1:
	s_sub_u32 s11, s10, 0x400
	s_lshr_b32 s19, s11, 4
	s_mul_i32 s19, s19, 0xab
	s_lshr_b32 s19, s19, 9
	s_mul_i32 s18, s19, 48
	s_sub_u32 s18, s11, s18
	v_readlane_b32 s12, v250, 34
	v_readlane_b32 s13, v250, 35
	v_readlane_b32 s22, v250, 32
	v_readlane_b32 s23, v250, 33
	s_movk_i32 s14, 0x3000
	s_movk_i32 s15, 0x800
	s_mov_b32 s20, 0x1000000
	s_mov_b32 s26, 1
.Ldw_go:
	s_lshl_b32 s21, s19, 5
	s_mul_i32 s24, s21, s14
	s_lshl_b32 s25, s18, 8
	s_add_u32 s24, s24, s25
	s_add_u32 s12, s12, s24
	s_addc_u32 s13, s13, 0
	s_lshl_b32 s25, s18, 6
	v_add_u32_e32 v1, s25, v0
	v_mul_lo_u32 v4, v1, s15
	s_lshl_b32 s25, s19, 6
	s_add_u32 s16, s44, s20
	s_addc_u32 s17, s45, 0
	v_add_u32_e32 v4, s25, v4
	global_load_dword v8, v2, s[12:13] nt
	s_add_u32 s12, s12, s14
	s_addc_u32 s13, s13, 0
	global_load_dword v9, v2, s[12:13] nt
	s_add_u32 s12, s12, s14
	s_addc_u32 s13, s13, 0
	global_load_dword v10, v2, s[12:13] nt
	s_add_u32 s12, s12, s14
	s_addc_u32 s13, s13, 0
	global_load_dword v11, v2, s[12:13] nt
	s_add_u32 s12, s12, s14
	s_addc_u32 s13, s13, 0
	global_load_dword v12, v2, s[12:13] nt
	s_add_u32 s12, s12, s14
	s_addc_u32 s13, s13, 0
	global_load_dword v13, v2, s[12:13] nt
	s_add_u32 s12, s12, s14
	s_addc_u32 s13, s13, 0
	global_load_dword v14, v2, s[12:13] nt
	s_add_u32 s12, s12, s14
	s_addc_u32 s13, s13, 0
	global_load_dword v15, v2, s[12:13] nt
	s_add_u32 s12, s12, s14
	s_addc_u32 s13, s13, 0
	global_load_dword v16, v2, s[12:13] nt
	s_add_u32 s12, s12, s14
	s_addc_u32 s13, s13, 0
	global_load_dword v17, v2, s[12:13] nt
	s_add_u32 s12, s12, s14
	s_addc_u32 s13, s13, 0
	global_load_dword v18, v2, s[12:13] nt
	s_add_u32 s12, s12, s14
	s_addc_u32 s13, s13, 0
	global_load_dword v19, v2, s[12:13] nt
	s_add_u32 s12, s12, s14
	s_addc_u32 s13, s13, 0
	global_load_dword v20, v2, s[12:13] nt
	s_add_u32 s12, s12, s14
	s_addc_u32 s13, s13, 0
	global_load_dword v21, v2, s[12:13] nt
	s_add_u32 s12, s12, s14
	s_addc_u32 s13, s13, 0
	global_load_dword v22, v2, s[12:13] nt
	s_add_u32 s12, s12, s14
	s_addc_u32 s13, s13, 0
	global_load_dword v23, v2, s[12:13] nt
	s_add_u32 s12, s12, s14
	s_addc_u32 s13, s13, 0
	global_load_dword v24, v2, s[12:13] nt
	s_add_u32 s12, s12, s14
	s_addc_u32 s13, s13, 0
	global_load_dword v25, v2, s[12:13] nt
	s_add_u32 s12, s12, s14
	s_addc_u32 s13, s13, 0
	global_load_dword v26, v2, s[12:13] nt
	s_add_u32 s12, s12, s14
	s_addc_u32 s13, s13, 0
	global_load_dword v27, v2, s[12:13] nt
	s_add_u32 s12, s12, s14
	s_addc_u32 s13, s13, 0
	global_load_dword v28, v2, s[12:13] nt
	s_add_u32 s12, s12, s14
	s_addc_u32 s13, s13, 0
	global_load_dword v29, v2, s[12:13] nt
	s_add_u32 s12, s12, s14
	s_addc_u32 s13, s13, 0
	global_load_dword v30, v2, s[12:13] nt
	s_add_u32 s12, s12, s14
	s_addc_u32 s13, s13, 0
	global_load_dword v31, v2, s[12:13] nt
	s_add_u32 s12, s12, s14
	s_addc_u32 s13, s13, 0
	global_load_dword v32, v2, s[12:13] nt
	s_add_u32 s12, s12, s14
	s_addc_u32 s13, s13, 0
	global_load_dword v33, v2, s[12:13] nt
	s_add_u32 s12, s12, s14
	s_addc_u32 s13, s13, 0
	global_load_dword v34, v2, s[12:13] nt
	s_add_u32 s12, s12, s14
	s_addc_u32 s13, s13, 0
	global_load_dword v35, v2, s[12:13] nt
	s_add_u32 s12, s12, s14
	s_addc_u32 s13, s13, 0
	global_load_dword v36, v2, s[12:13] nt
	s_add_u32 s12, s12, s14
	s_addc_u32 s13, s13, 0
	global_load_dword v37, v2, s[12:13] nt
	s_add_u32 s12, s12, s14
	s_addc_u32 s13, s13, 0
	global_load_dword v38, v2, s[12:13] nt
	s_add_u32 s12, s12, s14
	s_addc_u32 s13, s13, 0
	global_load_dword v39, v2, s[12:13] nt
	s_cmp_eq_u32 s26, 0
	s_cbranch_scc1 .Ldw_nogain
	s_lshl_b32 s25, s21, 2
	s_add_u32 s22, s22, s25
	s_addc_u32 s23, s23, 0
	s_load_dwordx16 s[48:63], s[22:23], 0x0
	s_waitcnt vmcnt(16) lgkmcnt(0)
	v_mul_f32_e32 v8, s48, v8
	v_mul_f32_e32 v9, s49, v9
	v_mul_f32_e32 v10, s50, v10
	v_mul_f32_e32 v11, s51, v11
	v_mul_f32_e32 v12, s52, v12
	v_mul_f32_e32 v13, s53, v13
	v_mul_f32_e32 v14, s54, v14
	v_mul_f32_e32 v15, s55, v15
	v_mul_f32_e32 v16, s56, v16
	v_mul_f32_e32 v17, s57, v17
	v_mul_f32_e32 v18, s58, v18
	v_mul_f32_e32 v19, s59, v19
	v_mul_f32_e32 v20, s60, v20
	v_mul_f32_e32 v21, s61, v21
	v_mul_f32_e32 v22, s62, v22
	v_mul_f32_e32 v23, s63, v23
	s_nop 0
	s_load_dwordx16 s[48:63], s[22:23], 0x40
	s_waitcnt vmcnt(0) lgkmcnt(0)
	v_mul_f32_e32 v24, s48, v24
	v_mul_f32_e32 v25, s49, v25
	v_mul_f32_e32 v26, s50, v26
	v_mul_f32_e32 v27, s51, v27
	v_mul_f32_e32 v28, s52, v28
	v_mul_f32_e32 v29, s53, v29
	v_mul_f32_e32 v30, s54, v30
	v_mul_f32_e32 v31, s55, v31
	v_mul_f32_e32 v32, s56, v32
	v_mul_f32_e32 v33, s57, v33
	v_mul_f32_e32 v34, s58, v34
	v_mul_f32_e32 v35, s59, v35
	v_mul_f32_e32 v36, s60, v36
	v_mul_f32_e32 v37, s61, v37
	v_mul_f32_e32 v38, s62, v38
	v_mul_f32_e32 v39, s63, v39
; __device__ __forceinline__ unsigned cvt_pk_bf16(float lo, float hi) { unsigned r; asm volatile("v_cvt_pk_bf16_f32 %0, %1, %2" : "=v"(r) : "v"(lo), "v"(hi)); return r; }
; __device__ __forceinline__ unsigned xb_ld(unsigned* p)              { return __hip_atomic_load(p, __ATOMIC_RELAXED, __HIP_MEMORY_SCOPE_AGENT); }
;     ...
;             w.x = cvt_pk_bf16(v0 * wscale, v1 * wscale); w.y = cvt_pk_bf16(v2 * wscale, v3 * wscale); w.z = cvt_pk_bf16(v4 * wscale, v5 * wscale); w.w = cvt_pk_bf16(v6 * wscale, v7 * wscale);
;         }
;         *(u32x4*)(dst + (size_t)n * K + k8 * 8) = w;
; __device__ __forceinline__ void xcd_barrier_complete(unsigned* bar, unsigned x, unsigned& nloc, unsigned& nx) {
;     const unsigned G = gridDim.x * gridDim.y * gridDim.z;
;     unsigned sum, cnt, mine, sp = 0u;
;     for (;;) {
;         sum = 0u; cnt = 0u; mine = 0u;
; #pragma unroll
;         for (unsigned j = 0; j < 16; ++j) { const unsigned c = xb_ld(&bar[XB_XCNT(j)]); sum += c; cnt += (c > 0u) ? 1u : 0u; mine = (j == x) ? c : mine; }
;         if (sum == G) break;
;         __builtin_amdgcn_s_sleep(1);
;         if ((++sp & 255u) == 0u) { if (xb_ld(&bar[XB_TMO])) break; if (sp > XB_SPIN_CAP) { atomicAdd(&bar[XB_TMO], 1u); break; } }
;     }
;     nloc = mine > 0u ? mine : 1u; nx = cnt > 0u ? cnt : 1u;
; }
; __device__ __forceinline__ void xcd_barrier(const XcdBarrier& b) {
;     asm volatile("s_waitcnt vmcnt(0)" ::: "memory");
;     __syncthreads();
;     if (threadIdx.x == 0) {
;         unsigned* bar = b.bar;
;         __builtin_amdgcn_s_waitcnt(0);
;         unsigned nloc = b.st[0], nx = b.st[1];
;         if (nloc == 0u) { xcd_barrier_complete(bar, b.x, nloc, nx); b.st[0] = nloc; b.st[1] = nx; }
.Ldw_nogain:
	s_waitcnt vmcnt(0)
	v_cvt_pk_bf16_f32 v8, v8, v9
	v_cvt_pk_bf16_f32 v9, v10, v11
	v_cvt_pk_bf16_f32 v10, v12, v13
	v_cvt_pk_bf16_f32 v11, v14, v15
	v_cvt_pk_bf16_f32 v12, v16, v17
	v_cvt_pk_bf16_f32 v13, v18, v19
	v_cvt_pk_bf16_f32 v14, v20, v21
	v_cvt_pk_bf16_f32 v15, v22, v23
	v_cvt_pk_bf16_f32 v16, v24, v25
	v_cvt_pk_bf16_f32 v17, v26, v27
	v_cvt_pk_bf16_f32 v18, v28, v29
	v_cvt_pk_bf16_f32 v19, v30, v31
	v_cvt_pk_bf16_f32 v20, v32, v33
	v_cvt_pk_bf16_f32 v21, v34, v35
	v_cvt_pk_bf16_f32 v22, v36, v37
	v_cvt_pk_bf16_f32 v23, v38, v39
	global_store_dwordx4 v4, v[8:11], s[16:17]
	global_store_dwordx4 v4, v[12:15], s[16:17] offset:16
	global_store_dwordx4 v4, v[16:19], s[16:17] offset:32
	global_store_dwordx4 v4, v[20:23], s[16:17] offset:48
	s_addk_i32 s10, 0x200
	s_branch .Ldw_loop
.Ldw_end:
	v_readlane_b32 s0, v251, 0
	v_readlane_b32 s10, v251, 1
	v_readlane_b32 s11, v251, 2
	v_readlane_b32 s12, v251, 3
	v_readlane_b32 s13, v251, 4
	v_readlane_b32 s14, v251, 5
	v_readlane_b32 s15, v251, 6
	v_readlane_b32 s16, v251, 7
	v_readlane_b32 s17, v251, 8
	v_readlane_b32 s18, v251, 9
	v_readlane_b32 s19, v251, 10
	v_readlane_b32 s20, v251, 11
	v_readlane_b32 s21, v251, 12
	v_readlane_b32 s22, v251, 13
	v_readlane_b32 s23, v251, 14
	v_readlane_b32 s24, v251, 15
	v_readlane_b32 s25, v251, 16
	v_readlane_b32 s26, v251, 17
	v_readlane_b32 s48, v251, 18
	v_readlane_b32 s49, v251, 19
	v_readlane_b32 s50, v251, 20
	v_readlane_b32 s51, v251, 21
	v_readlane_b32 s52, v251, 22
	v_readlane_b32 s53, v251, 23
	v_readlane_b32 s54, v251, 24
	v_readlane_b32 s55, v251, 25
	v_readlane_b32 s56, v251, 26
	v_readlane_b32 s57, v251, 27
	v_readlane_b32 s58, v251, 28
	v_readlane_b32 s59, v251, 29
	v_readlane_b32 s60, v251, 30
	v_readlane_b32 s61, v251, 31
	v_readlane_b32 s62, v251, 32
	v_readlane_b32 s63, v251, 33
	s_nop 0
.Ldw_done:
.LBB0_239:
	s_cmp_gt_i32 s47, 2
	s_cselect_b64 s[0:1], -1, 0
	s_and_b64 s[4:5], s[8:9], s[0:1]
	s_andn2_b64 vcc, exec, s[4:5]
	s_cbranch_vccnz .LBB0_293
	s_waitcnt vmcnt(0)
	s_waitcnt vmcnt(0) lgkmcnt(0)
	s_barrier
	s_mov_b64 s[4:5], exec
	v_readlane_b32 s6, v250, 2
	v_readlane_b32 s7, v250, 3
	s_and_b64 s[6:7], s[4:5], s[6:7]
	s_mov_b64 exec, s[6:7]
	s_cbranch_execz .LBB0_292
	s_add_i32 s3, 0, 0x26ff0
	v_mov_b32_e32 v0, s3
	s_waitcnt vmcnt(0) expcnt(0) lgkmcnt(0)
	ds_read_b32 v2, v0
	s_add_i32 s3, 0, 0x26ff4
	v_mov_b32_e32 v0, s3
	ds_read_b32 v0, v0
	s_waitcnt lgkmcnt(1)
	v_cmp_ne_u32_e32 vcc, 0, v2
	s_cbranch_vccnz .LBB0_256
	s_add_u32 s6, s44, 0x1f70e200
	s_addc_u32 s7, s45, 0
	s_add_u32 s8, s44, 0x1f70e400
	s_addc_u32 s9, s45, 0
	s_add_u32 s10, s44, 0x1f70e500
	s_addc_u32 s11, s45, 0
	s_add_u32 s12, s44, 0x1f70e600
	s_addc_u32 s13, s45, 0
	s_add_u32 s14, s44, 0x1f70e700
	s_addc_u32 s15, s45, 0
	s_add_u32 s16, s44, 0x1f70e800
	s_addc_u32 s17, s45, 0
	s_add_u32 s18, s44, 0x1f70e900
	s_addc_u32 s19, s45, 0
	s_add_u32 s20, s44, 0x1f70ea00
	s_addc_u32 s21, s45, 0
	s_add_u32 s22, s44, 0x1f70eb00
	s_addc_u32 s23, s45, 0
	s_add_u32 s24, s44, 0x1f70ec00
	s_addc_u32 s25, s45, 0
	s_add_u32 s26, s44, 0x1f70ed00
	s_addc_u32 s27, s45, 0
	s_add_u32 s28, s44, 0x1f70ee00
	s_addc_u32 s29, s45, 0
	s_add_u32 s30, s44, 0x1f70ef00
	s_addc_u32 s31, s45, 0
	s_add_u32 s34, s44, 0x1f70f000
	s_addc_u32 s35, s45, 0
	s_add_u32 s36, s44, 0x1f70f100
	s_addc_u32 s37, s45, 0
	s_add_u32 s38, s44, 0x1f70f200
	v_readlane_b32 s3, v250, 0
	s_addc_u32 s39, s45, 0
	s_mul_i32 s3, s95, s3
	s_add_u32 s48, s44, 0x1f70f300
	s_mul_i32 s3, s3, s94
	s_addc_u32 s49, s45, 0
	s_mov_b32 s33, 1
	v_mov_b32_e32 v16, 0
	s_branch .LBB0_244

; #define LAS __attribute__((address_space(3)))
; __global__ void __launch_bounds__(NTHR) mega(Params p) {
;     extern __shared__ __attribute__((aligned(16))) unsigned char lds_raw[];
;     LAS unsigned char* L = (LAS unsigned char*)lds_raw;
	.amdhsa_kernel _Z4mega6Params
		.amdhsa_group_segment_fixed_size 0
		.amdhsa_private_segment_fixed_size 0
		.amdhsa_kernarg_size 480
		.amdhsa_user_sgpr_count 2
		.amdhsa_user_sgpr_dispatch_ptr 0
		.amdhsa_user_sgpr_queue_ptr 0
		.amdhsa_user_sgpr_kernarg_segment_ptr 1
		.amdhsa_user_sgpr_dispatch_id 0
		.amdhsa_user_sgpr_kernarg_preload_length 0
		.amdhsa_user_sgpr_kernarg_preload_offset 0
		.amdhsa_user_sgpr_private_segment_size 0
		.amdhsa_uses_dynamic_stack 0
		.amdhsa_enable_private_segment 0
		.amdhsa_system_sgpr_workgroup_id_x 1
		.amdhsa_system_sgpr_workgroup_id_y 0
		.amdhsa_system_sgpr_workgroup_id_z 0
		.amdhsa_system_sgpr_workgroup_info 0
		.amdhsa_system_vgpr_workitem_id 2
		.amdhsa_next_free_vgpr 252
		.amdhsa_next_free_sgpr 102
		.amdhsa_accum_offset 252
		.amdhsa_reserve_vcc 1
		.amdhsa_float_round_mode_32 0
		.amdhsa_float_round_mode_16_64 0
		.amdhsa_float_denorm_mode_32 3
		.amdhsa_float_denorm_mode_16_64 3
		.amdhsa_dx10_clamp 1
		.amdhsa_ieee_mode 1
		.amdhsa_fp16_overflow 0
		.amdhsa_tg_split 0
		.amdhsa_exception_fp_ieee_invalid_op 0
		.amdhsa_exception_fp_denorm_src 0
		.amdhsa_exception_fp_ieee_div_zero 0
		.amdhsa_exception_fp_ieee_overflow 0
		.amdhsa_exception_fp_ieee_underflow 0
		.amdhsa_exception_fp_ieee_inexact 0
		.amdhsa_exception_int_div_zero 0
	.end_amdhsa_kernel

; #define LAS __attribute__((address_space(3)))
; __global__ void __launch_bounds__(NTHR) mega(Params p) {
;     extern __shared__ __attribute__((aligned(16))) unsigned char lds_raw[];
;     LAS unsigned char* L = (LAS unsigned char*)lds_raw;
amdhsa.kernels:
  - .agpr_count:     0
    .args:
      - .offset:         0
        .size:           224
        .value_kind:     by_value
      - .offset:         224
        .size:           4
        .value_kind:     hidden_block_count_x
      - .offset:         228
        .size:           4
        .value_kind:     hidden_block_count_y
      - .offset:         232
        .size:           4
        .value_kind:     hidden_block_count_z
      - .offset:         236
        .size:           2
        .value_kind:     hidden_group_size_x
      - .offset:         238
        .size:           2
        .value_kind:     hidden_group_size_y
      - .offset:         240
        .size:           2
        .value_kind:     hidden_group_size_z
      - .offset:         242
        .size:           2
        .value_kind:     hidden_remainder_x
      - .offset:         244
        .size:           2
        .value_kind:     hidden_remainder_y
      - .offset:         246
        .size:           2
        .value_kind:     hidden_remainder_z
      - .offset:         264
        .size:           8
        .value_kind:     hidden_global_offset_x
      - .offset:         272
        .size:           8
        .value_kind:     hidden_global_offset_y
      - .offset:         280
        .size:           8
        .value_kind:     hidden_global_offset_z
      - .offset:         288
        .size:           2
        .value_kind:     hidden_grid_dims
      - .offset:         312
        .size:           8
        .value_kind:     hidden_multigrid_sync_arg
      - .offset:         344
        .size:           4
        .value_kind:     hidden_dynamic_lds_size
    .group_segment_fixed_size: 0
    .kernarg_segment_align: 8
    .kernarg_segment_size: 480
    .language:       OpenCL C
    .language_version:
      - 2
      - 0
    .max_flat_workgroup_size: 512
    .name:           _Z4mega6Params
    .private_segment_fixed_size: 0
    .sgpr_count:     108
    .sgpr_spill_count: 58
    .symbol:         _Z4mega6Params.kd
    .uniform_work_group_size: 1
    .uses_dynamic_stack: false
    .vgpr_count:     252
    .vgpr_spill_count: 0
    .wavefront_size: 64
